# mLSTM: VTW fragment reads issued right after barrier 1 (latency hidden under S^T work); dword L2 warm loads
# speedup vs baseline: 1.0200x; 1.0200x over previous
; #define LAS __attribute__((address_space(3)))
; #define MFMA16(a, b, c) __builtin_amdgcn_mfma_f32_16x16x32_bf16((a), (b), (c), 0, 0, 0)
; __device__ __forceinline__ void mlstm_item(const Args& a, LAS unsigned char* L, bool sample, int b, int hh, int sl, bool dry = false) {
;     ...
;         {
;             typedef short v4i16_t __attribute__((ext_vector_type(4)));
;             v4i16_t tl[2], th[2]; bf16x8 Bv[5];
; #pragma unroll
;             for (int kti = 0; kti < 2; ++kti) { const int kt = 2 * wave + kti;
;                 tl[kti] = __builtin_amdgcn_ds_read_tr16_b64_v4i16((LAS v4i16_t*)(L + L_KS + (g * 8 + (lr >> 2)) * 528 + (kt * 16 + 4 * (lr & 3)) * 2));
;                 th[kti] = __builtin_amdgcn_ds_read_tr16_b64_v4i16((LAS v4i16_t*)(L + L_KS + (g * 8 + 4 + (lr >> 2)) * 528 + (kt * 16 + 4 * (lr & 3)) * 2)); }
; #pragma unroll
;             for (int vt = 0; vt < 5; ++vt) Bv[vt] = *(const LAS bf16x8*)(L + L_VTW + (vt * 16 + lr) * 80 + g * 16);
; #pragma unroll
;             for (int kti = 0; kti < 2; ++kti) { const bf16x8 A = (bf16x8){tl[kti][0], tl[kti][1], tl[kti][2], tl[kti][3], th[kti][0], th[kti][1], th[kti][2], th[kti][3]};
; #pragma unroll
;                 for (int vt = 0; vt < 5; ++vt) Cacc[kti][vt] = MFMA16(A, Bv[vt], Cacc[kti][vt] * dL); }
;         }
.LBB0_661:
	ds_read_b64_tr_b16 v[58:59], v97 offset:19008
	s_waitcnt lgkmcnt(1)
	ds_read_b64_tr_b16 v[56:57], v97 offset:16896
	ds_read_b64_tr_b16 v[116:117], v97 offset:16912
	ds_read_b64_tr_b16 v[118:119], v97 offset:19024
	ds_read_b128 v[190:193], v239
	ds_read_b128 v[194:197], v239 offset:32
	ds_read_b128 v[198:201], v239 offset:64
	ds_read_b128 v[202:205], v239 offset:96
	ds_read_b128 v[206:209], v239 offset:128
	ds_read_b128 v[210:213], v239 offset:160
	ds_read_b128 v[214:217], v239 offset:192
	ds_read_b128 v[218:221], v239 offset:224
	v_pk_mul_f32 v[38:39], v[38:39], v[76:77] op_sel_hi:[1,0]
	v_pk_mul_f32 v[36:37], v[36:37], v[76:77] op_sel_hi:[1,0]
	v_pk_mul_f32 v[54:55], v[54:55], v[76:77] op_sel_hi:[1,0]
	v_pk_mul_f32 v[52:53], v[52:53], v[76:77] op_sel_hi:[1,0]
	v_pk_mul_f32 v[50:51], v[50:51], v[76:77] op_sel_hi:[1,0]
	v_pk_mul_f32 v[48:49], v[48:49], v[76:77] op_sel_hi:[1,0]
	v_pk_mul_f32 v[46:47], v[46:47], v[76:77] op_sel_hi:[1,0]
	v_pk_mul_f32 v[44:45], v[44:45], v[76:77] op_sel_hi:[1,0]
	v_pk_mul_f32 v[42:43], v[42:43], v[76:77] op_sel_hi:[1,0]
	v_pk_mul_f32 v[40:41], v[40:41], v[76:77] op_sel_hi:[1,0]
	s_waitcnt lgkmcnt(10)
	v_mfma_f32_16x16x32_bf16 v[36:39], v[56:59], v[4:7], v[36:39]
	v_mul_f32_e64 v34, v34, v76
	v_mul_f32_e64 v35, v35, v76
	v_pk_mul_f32 v[32:33], v[32:33], v[76:77] op_sel_hi:[1,0]
	v_pk_mul_f32 v[30:31], v[30:31], v[76:77] op_sel_hi:[1,0]
	s_waitcnt lgkmcnt(10)
	v_mfma_f32_16x16x32_bf16 v[52:55], v[56:59], v[8:11], v[52:55]
	v_mul_f32_e64 v28, v28, v76
	v_mul_f32_e64 v29, v29, v76
	v_pk_mul_f32 v[26:27], v[26:27], v[76:77] op_sel_hi:[1,0]
	v_pk_mul_f32 v[24:25], v[24:25], v[76:77] op_sel_hi:[1,0]
	s_waitcnt lgkmcnt(10)
	v_mfma_f32_16x16x32_bf16 v[48:51], v[56:59], v[12:15], v[48:51]
	v_mul_f32_e64 v22, v22, v76
	v_mul_f32_e64 v23, v23, v76
	v_pk_mul_f32 v[20:21], v[20:21], v[76:77] op_sel_hi:[1,0]
	v_pk_mul_f32 v[18:19], v[18:19], v[76:77] op_sel_hi:[1,0]
	s_waitcnt lgkmcnt(10)
	v_mfma_f32_16x16x32_bf16 v[44:47], v[56:59], v[240:243], v[44:47]
	v_mul_f32_e64 v16, v16, v76
	v_mul_f32_e64 v17, v17, v76
	s_waitcnt lgkmcnt(0)
	s_barrier
	s_add_u32 s98, s100, s70
	s_addc_u32 s99, s101, s71
	s_add_u32 s98, s98, 0x70000
	s_addc_u32 s99, s99, 0
	s_lshl_b32 m0, s55, 10
	s_nop 0
	global_load_lds_dwordx4 v229, s[98:99]
	s_add_u32 m0, m0, 0x2000
	s_nop 0
	global_load_lds_dwordx4 v230, s[98:99]
	s_add_u32 m0, m0, 0x2000
	s_nop 0
	global_load_lds_dwordx4 v231, s[98:99]
	s_add_u32 m0, m0, 0x2000
	s_nop 0
	global_load_lds_dwordx4 v232, s[98:99]
	s_cmp_lg_u32 s55, 0
	s_cbranch_scc1 .Ldma_skip_loop
	s_mov_b32 m0, 0x8000
	s_nop 0
	global_load_lds_dwordx4 v233, s[98:99]
; #define LAS __attribute__((address_space(3)))
; #define MFMA16(a, b, c) __builtin_amdgcn_mfma_f32_16x16x32_bf16((a), (b), (c), 0, 0, 0)
; __device__ __forceinline__ void mlstm_item(const Args& a, LAS unsigned char* L, bool sample, int b, int hh, int sl, bool dry = false) {
;     ...
; #pragma unroll
;             for (int vt = 0; vt < 5; ++vt) Bv[vt] = *(const LAS bf16x8*)(L + L_VTW + (vt * 16 + lr) * 80 + g * 16);
; #pragma unroll
;             for (int kti = 0; kti < 2; ++kti) { const bf16x8 A = (bf16x8){tl[kti][0], tl[kti][1], tl[kti][2], tl[kti][3], th[kti][0], th[kti][1], th[kti][2], th[kti][3]};
; #pragma unroll
;                 for (int vt = 0; vt < 5; ++vt) Cacc[kti][vt] = MFMA16(A, Bv[vt], Cacc[kti][vt] * dL); }
;         }
;         LDS_BARRIER();
;         {
;             const int tt = wave & 1, vt = wave >> 1, t = tt * 16 + lr;
;             const bf16x8 Bs = *(const LAS bf16x8*)(L + L_SS + t * 80 + g * 16);
;             const f32x4 z4 = (f32x4){0.f, 0.f, 0.f, 0.f};
;             const bf16x8 Av = *(const LAS bf16x8*)(L + L_VT + (vt * 16 + lr) * 80 + g * 16);
;             bf16x8 Af[8], Bf[8];
; #pragma unroll
;             for (int kk = 0; kk < 8; ++kk) { Af[kk] = *(const LAS bf16x8*)(L + L_CS + (vt * 16 + lr) * 528 + kk * 64 + g * 16); Bf[kk] = *(const LAS bf16x8*)(L + L_QS + t * 528 + kk * 64 + g * 16); }
;             __builtin_amdgcn_sched_barrier(0);
;             f32x4 sM = MFMA16(Av, Bs, z4);
;             f32x4 cM = z4;
; #pragma unroll
;             for (int kk = 0; kk < 8; ++kk) cM = MFMA16(Af[kk], Bf[kk], cM);
;             const float d0 = __expf(m0c + GFM[c * 32 + t]), en = GEN[c * 32 + t];
;             const LAS float* NQ = (const LAS float*)(L + L_NQ);
;             const float nq = (NQ[t] + NQ[32 + t]) + d0 * (NQ[64 + t] + NQ[96 + t]);
;             const float inv = __builtin_amdgcn_rcpf(fmaxf(fabsf(nq), en));
;             float hv[4];
; #pragma unroll
;             for (int j = 0; j < 4; ++j) hv[j] = (sM[j] + d0 * cM[j]) * inv;
;             if (dry) *(u32x2*)((bf16_t*)a.out + (size_t)(rowbase + c * 32 + t) * 1024 + hh * 256 + sl * 64 + vt * 16 + g * 4) = (u32x2){pk2(hv[0], hv[1]), pk2(hv[2], hv[3])};
;             else *(u32x2*)(U + (size_t)(rowbase + c * 32 + t) * LDU + C_V + hh * 256 + sl * 64 + vt * 16 + g * 4) = (u32x2){pk2(hv[0], hv[1]), pk2(hv[2], hv[3])};
;         }
;         LDS_BARRIER();
;         WRITE_CS();
.Ldma_skip_loop:
	s_waitcnt lgkmcnt(0)
	v_mfma_f32_16x16x32_bf16 v[40:43], v[56:59], v[244:247], v[40:43]
	v_add_u32_e32 v58, v70, v99
	v_add_u32_e32 v57, v104, v222
	v_mfma_f32_16x16x32_bf16 v[32:35], v[116:119], v[4:7], v[32:35]
	v_mfma_f32_16x16x32_bf16 v[28:31], v[116:119], v[8:11], v[28:31]
	v_mfma_f32_16x16x32_bf16 v[24:27], v[116:119], v[12:15], v[24:27]
	v_mfma_f32_16x16x32_bf16 v[20:23], v[116:119], v[240:243], v[20:23]
	v_mfma_f32_16x16x32_bf16 v[16:19], v[116:119], v[244:247], v[16:19]
	ds_read_b128 v[116:119], v91 offset:46592
	ds_read_b128 v[120:123], v58 offset:33792
	ds_read_b128 v[124:127], v90 offset:49152
	ds_read_b128 v[132:135], v90 offset:49184
	ds_read_b128 v[140:143], v90 offset:49216
	ds_read_b128 v[148:151], v90 offset:49248
	ds_read_b128 v[156:159], v90 offset:49280
	ds_read_b128 v[164:167], v90 offset:49312
	ds_read_b128 v[172:175], v90 offset:49344
	ds_read_b128 v[182:185], v90 offset:49376
	s_waitcnt lgkmcnt(7)
	v_mfma_f32_16x16x32_bf16 v[124:127], v[124:127], v[190:193], 0
	v_add_u32_e32 v56, 0, v110
	v_add_u32_e32 v59, 0x16500, v56
	ds_read_b32 v59, v59
	s_waitcnt lgkmcnt(7)
	v_mfma_f32_16x16x32_bf16 v[124:127], v[132:135], v[194:197], v[124:127]
	v_add_u32_e32 v56, 0x1a500, v56
	ds_read2_b32 v[128:129], v89 offset1:32
	ds_read_b32 v56, v56
	ds_read2_b32 v[130:131], v89 offset0:64 offset1:96
	s_waitcnt lgkmcnt(9)
	v_mfma_f32_16x16x32_bf16 v[124:127], v[140:143], v[198:201], v[124:127]
	s_waitcnt lgkmcnt(3)
	v_add_f32_e32 v59, v115, v59
	v_mul_f32_e32 v59, 0x3fb8aa3b, v59
	v_exp_f32_e32 v59, v59
	v_mfma_f32_16x16x32_bf16 v[124:127], v[148:151], v[202:205], v[124:127]
	s_waitcnt lgkmcnt(2)
	v_mov_b32_e32 v132, v128
	s_waitcnt lgkmcnt(0)
	v_mov_b32_e32 v133, v130
	v_mov_b32_e32 v130, v129
	v_mfma_f32_16x16x32_bf16 v[124:127], v[156:159], v[206:209], v[124:127]
	v_add_f32_e64 v128, v132, v130
	v_add_f32_e64 v129, v133, v131
	v_max_f32_e32 v56, v56, v56
	v_fmac_f32_e32 v128, v59, v129
	v_mfma_f32_16x16x32_bf16 v[124:127], v[164:167], v[210:213], v[124:127]
	v_max_f32_e64 v56, |v128|, v56
	v_rcp_f32_e32 v56, v56
	s_lshl_b32 s42, s53, 1
	v_mfma_f32_16x16x32_bf16 v[124:127], v[172:175], v[214:217], v[124:127]
	s_mov_b32 s59, s43
	s_add_i32 s16, s16, 4
	s_add_u32 s70, s70, 0x70000
	v_mfma_f32_16x16x32_bf16 v[124:127], v[182:185], v[218:221], v[124:127]
	s_addc_u32 s71, s71, 0
	v_add_u32_e32 v114, 0x80, v114
	v_add_u32_e32 v110, 0x80, v110
	v_mfma_f32_16x16x32_bf16 v[116:119], v[120:123], v[116:119], 0
	v_cvt_pk_bf16_f32 v120, v48, v49
	v_cvt_pk_bf16_f32 v121, v50, v51
	s_cmp_eq_u32 s70, 0x1b90000
	v_add_u32_e32 v111, 0x80, v111
	v_cvt_pk_bf16_f32 v122, v44, v45
	s_nop 5
	v_fma_f32 v76, v124, v59, v116
	v_fma_f32 v115, v125, v59, v117
	v_fma_f32 v116, v126, v59, v118
	v_fmac_f32_e32 v119, v127, v59
	v_mul_f32_e32 v76, v76, v56
	v_mul_f32_e32 v115, v115, v56
	v_mul_f32_e32 v117, v116, v56
	v_mul_f32_e32 v56, v119, v56
	v_mov_b64_e32 v[118:119], s[28:29]
	v_mad_i64_i32 v[118:119], s[72:73], v109, s84, v[118:119]
	v_lshl_add_u64 v[118:119], v[118:119], 0, s[42:43]
	v_lshl_add_u64 v[118:119], v[118:119], 0, s[58:59]
	v_lshl_add_u64 v[118:119], s[56:57], 1, v[118:119]
	v_lshl_add_u64 v[118:119], v[118:119], 0, v[60:61]
	v_add_co_u32_e32 v118, vcc, s85, v118
	v_cvt_pk_bf16_f32 v116, v76, v115
	v_cvt_pk_bf16_f32 v117, v117, v56
	v_add_u32_e32 v59, 0xc000, v113
	s_nop 0
	v_addc_co_u32_e32 v119, vcc, 0, v119, vcc
	global_store_dwordx2 v[118:119], v[116:117], off
	v_cvt_pk_bf16_f32 v116, v36, v37
	v_cvt_pk_bf16_f32 v117, v38, v39
	s_waitcnt lgkmcnt(0)
	s_barrier
	v_cvt_pk_bf16_f32 v126, v32, v33
	v_cvt_pk_bf16_f32 v127, v34, v35
	ds_write2_b64 v59, v[116:117], v[126:127] offset1:2
	v_cvt_pk_bf16_f32 v116, v28, v29
	v_cvt_pk_bf16_f32 v117, v30, v31
	v_add_u32_e32 v76, 0xe000, v113
	v_cvt_pk_bf16_f32 v118, v52, v53
	v_cvt_pk_bf16_f32 v119, v54, v55
	ds_write2_b64 v76, v[118:119], v[116:117] offset0:32 offset1:34
	v_cvt_pk_bf16_f32 v116, v24, v25
	v_cvt_pk_bf16_f32 v117, v26, v27
	ds_write2_b64 v85, v[120:121], v[116:117] offset1:2
	v_cvt_pk_bf16_f32 v116, v20, v21
	v_cvt_pk_bf16_f32 v117, v22, v23
	v_add_u32_e32 v115, 0xe000, v86
	v_add_u32_e32 v109, 32, v109
	v_cvt_pk_bf16_f32 v123, v46, v47
	v_cvt_pk_bf16_f32 v124, v40, v41
	v_cvt_pk_bf16_f32 v125, v42, v43
	ds_write2_b64 v115, v[122:123], v[116:117] offset0:32 offset1:34
	v_cvt_pk_bf16_f32 v116, v16, v17
	v_cvt_pk_bf16_f32 v117, v18, v19
	ds_write2_b64 v67, v[124:125], v[116:117] offset0:32 offset1:34
	s_cmp_eq_u32 s70, 0x1b90000
	s_cbranch_scc1 .LBB0_676

; #define LAS __attribute__((address_space(3)))
; #define MFMA16(a, b, c) __builtin_amdgcn_mfma_f32_16x16x32_bf16((a), (b), (c), 0, 0, 0)
; __device__ __forceinline__ void mlstm_item(const Args& a, LAS unsigned char* L, bool sample, int b, int hh, int sl, bool dry = false) {
;     ...
;         if (c + 1 < nchunks) PREFETCH(c + 1);
;         LDS_BARRIER();
;         const float dL = GDL[c], m0c = GM0[c];
;         if (wave < 4) {
;             const int st = wave >> 1, tt = wave & 1, t = tt * 16 + lr;
;             f32x4 s = (f32x4){0.f, 0.f, 0.f, 0.f};
;             if (!(st == 1 && tt == 0)) {
;                 bf16x8 Af[8], Bf[8];
; #pragma unroll
;                 for (int kk = 0; kk < 8; ++kk) { Af[kk] = *(const LAS bf16x8*)(L + L_KS + (st * 16 + lr) * 528 + kk * 64 + g * 16); Bf[kk] = *(const LAS bf16x8*)(L + L_QS + t * 528 + kk * 64 + g * 16); }
;                 __builtin_amdgcn_sched_barrier(0);
; #pragma unroll
;                 for (int kk = 0; kk < 8; ++kk) s = MFMA16(Af[kk], Bf[kk], s);
;             }
;             const float fmt = GFM[c * 32 + t];
;             const f32x4 as4 = *(const LAS f32x4*)(L + L_GAA + (c * 32 + st * 16 + g * 4) * 4);
;             float val[4];
; #pragma unroll
;             for (int j = 0; j < 4; ++j) { const int si = st * 16 + g * 4 + j; const float e = __expf(fminf(fmt + as4[j], 0.f)); val[j] = (si <= t) ? s[j] * e : 0.f; }
;             *(LAS u32x2*)(L + L_SS + t * 80 + (st * 16 + g * 4) * 2) = (u32x2){pk2(val[0], val[1]), pk2(val[2], val[3])};
;             float rsum = (val[0] + val[1]) + (val[2] + val[3]);
;             rsum += __shfl_xor(rsum, 16); rsum += __shfl_xor(rsum, 32);
;             if (g == 0) *(LAS float*)(L + L_NQ + (st * 32 + t) * 4) = rsum;
;         } else {
;             const int w4 = wave - 4, tt = w4 & 1, kh = w4 >> 1, t = tt * 16 + lr;
;             f32x4 cA = (f32x4){0.f, 0.f, 0.f, 0.f};
;             bf16x8 Af[4], Bf[4];
; #pragma unroll
;             for (int kk = 0; kk < 4; ++kk) { const int ko = (kh * 4 + kk) * 64 + g * 16; Af[kk] = *(const LAS bf16x8*)(L + L_CS + (64 + lr) * 528 + ko); Bf[kk] = *(const LAS bf16x8*)(L + L_QS + t * 528 + ko); }
;             __builtin_amdgcn_sched_barrier(0);
; #pragma unroll
;             for (int kk = 0; kk < 4; ++kk) cA = MFMA16(Af[kk], Bf[kk], cA);
;             if (g == 0) *(LAS float*)(L + L_NQ + (64 + kh * 32 + t) * 4) = cA[0];
;         }
.LBB0_665:
	s_or_b64 exec, exec, s[72:73]
	v_lshl_add_u64 v[8:9], v[74:75], 0, s[70:71]
	v_add_co_u32_e32 v0, vcc, 0x72000, v8
	s_nop 1
	v_addc_co_u32_e32 v1, vcc, 0, v9, vcc
	v_add_co_u32_e32 v8, vcc, 0xaa000, v8
	global_load_dword v2, v[0:1], off
	s_nop 0
	global_load_dword v3, v[0:1], off offset:2048
	v_addc_co_u32_e32 v9, vcc, 0, v9, vcc
	global_load_dword v0, v[8:9], off
	s_nop 0
	global_load_dword v1, v[8:9], off offset:2048
	s_and_saveexec_b64 s[72:73], s[0:1]
	s_cbranch_execz .LBB0_667
	v_lshl_add_u64 v[56:57], v[72:73], 0, s[70:71]
	v_add_co_u32_e32 v58, vcc, 0x73000, v56
	s_nop 1
	v_addc_co_u32_e32 v59, vcc, 0, v57, vcc
	v_add_co_u32_e32 v56, vcc, 0x76000, v56
	s_nop 1
	v_addc_co_u32_e32 v57, vcc, 0, v57, vcc
	global_load_dwordx2 v[62:63], v[58:59], off
	global_load_dwordx2 v[64:65], v[56:57], off offset:2048
.LBB0_667:
	s_or_b64 exec, exec, s[72:73]
	s_add_i32 s17, s16, 0
	s_add_i32 s42, s17, 0x1e600
	s_waitcnt lgkmcnt(0)
	s_barrier
	v_mov_b32_e32 v56, s42
	s_add_i32 s17, s17, 0x1e500
	v_mov_b32_e32 v57, s17
	ds_read_b32 v76, v56
	ds_read_b32 v115, v57
	ds_read_b128 v[4:7], v95 offset:40192
	ds_read_b128 v[8:11], v95 offset:41472
	ds_read_b128 v[12:15], v95 offset:42752
	ds_read_b128 v[240:243], v95 offset:44032
	ds_read_b128 v[244:247], v95 offset:45312
	s_mov_b64 s[72:73], -1
	s_and_b64 vcc, exec, s[68:69]
	s_cbranch_vccz .LBB0_671
	v_add_u32_e32 v132, v105, v103
	v_add_u32_e32 v140, v104, v103
	ds_read_b128 v[56:59], v132 offset:33792
	ds_read_b128 v[116:119], v132 offset:33824
	ds_read_b128 v[120:123], v140
	ds_read_b128 v[124:127], v140 offset:32
	ds_read_b128 v[128:131], v132 offset:33856
	ds_read_b128 v[132:135], v132 offset:33888
	ds_read_b128 v[136:139], v140 offset:64
	ds_read_b128 v[140:143], v140 offset:96
	s_waitcnt lgkmcnt(5)
	v_mfma_f32_16x16x32_bf16 v[56:59], v[56:59], v[120:123], 0
	s_waitcnt lgkmcnt(4)
	v_mfma_f32_16x16x32_bf16 v[56:59], v[116:119], v[124:127], v[56:59]
	s_waitcnt lgkmcnt(1)
	v_mfma_f32_16x16x32_bf16 v[56:59], v[128:131], v[136:139], v[56:59]
	s_waitcnt lgkmcnt(0)
	v_mfma_f32_16x16x32_bf16 v[56:59], v[132:135], v[140:143], v[56:59]
	s_and_saveexec_b64 s[72:73], s[4:5]
	s_nop 6
	v_add_u32_e32 v57, 0, v102
	v_add_u32_e32 v57, 0x1e800, v57
	ds_write_b32 v57, v56
	s_or_b64 exec, exec, s[72:73]
	s_mov_b64 s[72:73], 0
